# DIFF_IN epilogue: the 32 per-row RoPE table loads (each followed by vmcnt(0)) replaced by 16 loads issued before the chain
# speedup vs baseline: 1.0050x; 1.0050x over previous
.LBB0_846:
	s_and_b64 vcc, exec, s[0:1]
	s_cbranch_vccz .LBB0_827
	v_mov_b32_e32 v10, s84
	ds_read_b64 v[10:11], v10
	s_lshl_b32 s0, s8, 6
	s_ashr_i32 s1, s0, 31
	s_lshl_b64 s[0:1], s[0:1], 2
	v_and_b32_e32 v15, 64, v204
	s_waitcnt lgkmcnt(0)
	v_readfirstlane_b32 s70, v10
	v_readfirstlane_b32 s71, v11
	s_add_u32 s0, s70, s0
	s_addc_u32 s1, s71, s1
	global_load_dword v11, v197, s[0:1]
	global_load_dword v10, v197, s[0:1] offset:128
	v_xor_b32_e32 v14, 1, v204
	v_add_u32_e32 v15, 64, v15
	v_pk_mul_f32 v[12:13], v[86:87], v[86:87]
	v_cmp_lt_i32_e32 vcc, v14, v15
	v_add_f32_e32 v12, v13, v12
	s_cmp_eq_u32 s8, 1
	v_cndmask_b32_e32 v13, v204, v14, vcc
	v_lshlrev_b32_e32 v100, 2, v13
	ds_bpermute_b32 v13, v100, v12
	v_xor_b32_e32 v14, 2, v204
	v_cmp_lt_i32_e32 vcc, v14, v15
	s_cselect_b64 s[0:1], -1, 0
	s_xor_b64 s[70:71], s[4:5], -1
	v_cndmask_b32_e32 v14, v204, v14, vcc
	v_lshlrev_b32_e32 v101, 2, v14
	s_waitcnt lgkmcnt(0)
	v_add_f32_e32 v12, v12, v13
	ds_bpermute_b32 v13, v101, v12
	v_xor_b32_e32 v14, 4, v204
	v_cmp_lt_i32_e32 vcc, v14, v15
	s_and_b64 s[70:71], s[70:71], s[0:1]
	v_lshl_or_b32 v134, s72, 7, v140
	v_cndmask_b32_e32 v14, v204, v14, vcc
	v_lshlrev_b32_e32 v102, 2, v14
	s_waitcnt lgkmcnt(0)
	v_add_f32_e32 v12, v12, v13
	ds_bpermute_b32 v13, v102, v12
	v_xor_b32_e32 v14, 8, v204
	v_cmp_lt_i32_e32 vcc, v14, v15
	s_waitcnt lgkmcnt(0)
	v_add_f32_e32 v12, v12, v13
	v_cndmask_b32_e32 v14, v204, v14, vcc
	v_lshlrev_b32_e32 v103, 2, v14
	ds_bpermute_b32 v13, v103, v12
	v_xor_b32_e32 v14, 16, v204
	v_cmp_lt_i32_e32 vcc, v14, v15
	s_waitcnt lgkmcnt(0)
	v_add_f32_e32 v12, v12, v13
	v_cndmask_b32_e32 v14, v204, v14, vcc
	v_lshlrev_b32_e32 v104, 2, v14
	ds_bpermute_b32 v13, v104, v12
	s_and_b64 vcc, exec, s[70:71]
	s_waitcnt lgkmcnt(0)
	v_add_f32_e32 v12, v12, v13
	v_fmamk_f32 v12, v12, 0x3c800000, v196
	v_rsq_f32_e32 v12, v12
	v_add_u32_e32 v144, s69, v160
	v_lshl_or_b32 v144, v144, 5, v140
	v_lshlrev_b32_e32 v144, 3, v144
	global_load_dwordx2 v[144:145], v144, s[24:25]
	v_add_u32_e32 v146, s69, v168
	v_lshl_or_b32 v146, v146, 5, v140
	v_lshlrev_b32_e32 v146, 3, v146
	global_load_dwordx2 v[146:147], v146, s[24:25]
	v_add_u32_e32 v184, s69, v169
	v_lshl_or_b32 v184, v184, 5, v140
	v_lshlrev_b32_e32 v184, 3, v184
	global_load_dwordx2 v[184:185], v184, s[24:25]
	v_add_u32_e32 v186, s69, v170
	v_lshl_or_b32 v186, v186, 5, v140
	v_lshlrev_b32_e32 v186, 3, v186
	global_load_dwordx2 v[186:187], v186, s[24:25]
	v_add_u32_e32 v226, s69, v171
	v_lshl_or_b32 v226, v226, 5, v140
	v_lshlrev_b32_e32 v226, 3, v226
	global_load_dwordx2 v[226:227], v226, s[24:25]
	v_add_u32_e32 v230, s69, v172
	v_lshl_or_b32 v230, v230, 5, v140
	v_lshlrev_b32_e32 v230, 3, v230
	global_load_dwordx2 v[230:231], v230, s[24:25]
	v_add_u32_e32 v232, s69, v173
	v_lshl_or_b32 v232, v232, 5, v140
	v_lshlrev_b32_e32 v232, 3, v232
	global_load_dwordx2 v[232:233], v232, s[24:25]
	v_add_u32_e32 v234, s69, v174
	v_lshl_or_b32 v234, v234, 5, v140
	v_lshlrev_b32_e32 v234, 3, v234
	global_load_dwordx2 v[234:235], v234, s[24:25]
	v_add_u32_e32 v236, s69, v175
	v_lshl_or_b32 v236, v236, 5, v140
	v_lshlrev_b32_e32 v236, 3, v236
	global_load_dwordx2 v[236:237], v236, s[24:25]
	v_add_u32_e32 v238, s69, v176
	v_lshl_or_b32 v238, v238, 5, v140
	v_lshlrev_b32_e32 v238, 3, v238
	global_load_dwordx2 v[238:239], v238, s[24:25]
	v_add_u32_e32 v240, s69, v177
	v_lshl_or_b32 v240, v240, 5, v140
	v_lshlrev_b32_e32 v240, 3, v240
	global_load_dwordx2 v[240:241], v240, s[24:25]
	v_add_u32_e32 v242, s69, v178
	v_lshl_or_b32 v242, v242, 5, v140
	v_lshlrev_b32_e32 v242, 3, v242
	global_load_dwordx2 v[242:243], v242, s[24:25]
	v_add_u32_e32 v244, s69, v179
	v_lshl_or_b32 v244, v244, 5, v140
	v_lshlrev_b32_e32 v244, 3, v244
	global_load_dwordx2 v[244:245], v244, s[24:25]
	v_add_u32_e32 v246, s69, v180
	v_lshl_or_b32 v246, v246, 5, v140
	v_lshlrev_b32_e32 v246, 3, v246
	global_load_dwordx2 v[246:247], v246, s[24:25]
	v_add_u32_e32 v248, s69, v181
	v_lshl_or_b32 v248, v248, 5, v140
	v_lshlrev_b32_e32 v248, 3, v248
	global_load_dwordx2 v[248:249], v248, s[24:25]
	v_add_u32_e32 v250, s69, v182
	v_lshl_or_b32 v250, v250, 5, v140
	v_lshlrev_b32_e32 v250, 3, v250
	global_load_dwordx2 v[250:251], v250, s[24:25]
	s_waitcnt vmcnt(0)
	v_pk_mul_f32 v[12:13], v[10:11], v[12:13] op_sel_hi:[1,0]
	s_nop 0
	v_pk_mul_f32 v[14:15], v[86:87], v[12:13]
	s_cbranch_vccz .LBB0_849
	v_lshl_or_b32 v12, v148, 10, v134
	v_ashrrev_i32_e32 v13, 31, v12
	v_lshl_add_u64 v[12:13], v[12:13], 2, s[26:27]
	global_store_dword v[12:13], v15, off sc1
	global_store_dword v[12:13], v14, off offset:128 sc1
.LBB0_849:
	v_cndmask_b32_e64 v12, 0, 1, s[4:5]
	v_cmp_ne_u32_e64 s[0:1], 1, v12
	v_add_u32_e32 v12, s69, v160
	s_andn2_b64 vcc, exec, s[4:5]
	v_lshl_or_b32 v12, v12, 5, v140
	s_cbranch_vccnz .LBB0_851
	v_mov_b32_e32 v13, v135
	v_lshl_add_u64 v[24:25], v[12:13], 3, s[24:25]
	v_mov_b64_e32 v[24:25], v[144:145]
	v_pk_mul_f32 v[28:29], v[14:15], v[24:25] op_sel_hi:[0,1]
	v_pk_mul_f32 v[26:27], v[14:15], v[24:25] op_sel:[1,1] op_sel_hi:[1,0]
	v_pk_fma_f32 v[14:15], v[14:15], v[24:25], v[28:29] op_sel:[1,1,0] op_sel_hi:[1,0,1] neg_lo:[0,0,1] neg_hi:[0,0,1]
	s_nop 0
	v_add_f32_e32 v14, v26, v28

.LBB0_853:
	v_add_u32_e32 v13, s69, v168
	s_and_b64 vcc, exec, s[0:1]
	v_lshl_or_b32 v26, v13, 5, v140
	s_cbranch_vccnz .LBB0_855
	v_mov_b32_e32 v27, v135
	v_lshl_add_u64 v[30:31], v[26:27], 3, s[24:25]
	v_mov_b64_e32 v[30:31], v[146:147]
	v_pk_mul_f32 v[60:61], v[28:29], v[30:31] op_sel_hi:[0,1]
	v_pk_mul_f32 v[58:59], v[28:29], v[30:31] op_sel:[1,1] op_sel_hi:[1,0]
	v_pk_fma_f32 v[28:29], v[28:29], v[30:31], v[60:61] op_sel:[1,1,0] op_sel_hi:[1,0,1] neg_lo:[0,0,1] neg_hi:[0,0,1]
	s_nop 0
	v_add_f32_e32 v28, v58, v60

.LBB0_857:
	v_add_u32_e32 v13, s69, v169
	s_and_b64 vcc, exec, s[0:1]
	v_lshl_or_b32 v30, v13, 5, v140
	s_cbranch_vccnz .LBB0_859
	v_mov_b32_e32 v31, v135
	v_lshl_add_u64 v[60:61], v[30:31], 3, s[24:25]
	v_mov_b64_e32 v[60:61], v[184:185]
	v_pk_mul_f32 v[78:79], v[58:59], v[60:61] op_sel_hi:[0,1]
	v_pk_mul_f32 v[62:63], v[58:59], v[60:61] op_sel:[1,1] op_sel_hi:[1,0]
	v_pk_fma_f32 v[58:59], v[58:59], v[60:61], v[78:79] op_sel:[1,1,0] op_sel_hi:[1,0,1] neg_lo:[0,0,1] neg_hi:[0,0,1]
	s_nop 0
	v_add_f32_e32 v58, v62, v78

.LBB0_861:
	v_add_u32_e32 v13, s69, v170
	s_and_b64 vcc, exec, s[0:1]
	v_lshl_or_b32 v60, v13, 5, v140
	s_cbranch_vccnz .LBB0_863
	v_mov_b32_e32 v61, v135
	v_lshl_add_u64 v[74:75], v[60:61], 3, s[24:25]
	v_mov_b64_e32 v[74:75], v[186:187]
	v_pk_mul_f32 v[80:81], v[62:63], v[74:75] op_sel_hi:[0,1]
	v_pk_mul_f32 v[78:79], v[62:63], v[74:75] op_sel:[1,1] op_sel_hi:[1,0]
	v_pk_fma_f32 v[62:63], v[62:63], v[74:75], v[80:81] op_sel:[1,1,0] op_sel_hi:[1,0,1] neg_lo:[0,0,1] neg_hi:[0,0,1]
	s_nop 0
	v_add_f32_e32 v62, v78, v80

.LBB0_865:
	v_add_u32_e32 v13, s69, v171
	s_and_b64 vcc, exec, s[0:1]
	v_lshl_or_b32 v70, v13, 5, v140
	s_cbranch_vccnz .LBB0_867
	v_mov_b32_e32 v71, v135
	v_lshl_add_u64 v[78:79], v[70:71], 3, s[24:25]
	v_mov_b64_e32 v[78:79], v[226:227]
	v_pk_mul_f32 v[82:83], v[74:75], v[78:79] op_sel_hi:[0,1]
	v_pk_mul_f32 v[80:81], v[74:75], v[78:79] op_sel:[1,1] op_sel_hi:[1,0]
	v_pk_fma_f32 v[74:75], v[74:75], v[78:79], v[82:83] op_sel:[1,1,0] op_sel_hi:[1,0,1] neg_lo:[0,0,1] neg_hi:[0,0,1]
	s_nop 0
	v_add_f32_e32 v74, v80, v82

.LBB0_869:
	v_add_u32_e32 v13, s69, v172
	s_and_b64 vcc, exec, s[0:1]
	v_lshl_or_b32 v74, v13, 5, v140
	s_cbranch_vccnz .LBB0_871
	v_mov_b32_e32 v75, v135
	v_lshl_add_u64 v[72:73], v[74:75], 3, s[24:25]
	v_mov_b64_e32 v[72:73], v[230:231]
	v_pk_mul_f32 v[82:83], v[78:79], v[72:73] op_sel_hi:[0,1]
	v_pk_mul_f32 v[80:81], v[78:79], v[72:73] op_sel:[1,1] op_sel_hi:[1,0]
	v_pk_fma_f32 v[78:79], v[78:79], v[72:73], v[82:83] op_sel:[1,1,0] op_sel_hi:[1,0,1] neg_lo:[0,0,1] neg_hi:[0,0,1]
	s_nop 0
	v_add_f32_e32 v78, v80, v82

.LBB0_873:
	v_add_u32_e32 v13, s69, v173
	s_and_b64 vcc, exec, s[0:1]
	v_lshl_or_b32 v78, v13, 5, v140
	s_cbranch_vccnz .LBB0_875
	v_mov_b32_e32 v79, v135
	v_lshl_add_u64 v[76:77], v[78:79], 3, s[24:25]
	v_mov_b64_e32 v[76:77], v[232:233]
	v_pk_mul_f32 v[84:85], v[80:81], v[76:77] op_sel_hi:[0,1]
	v_pk_mul_f32 v[82:83], v[80:81], v[76:77] op_sel:[1,1] op_sel_hi:[1,0]
	v_pk_fma_f32 v[80:81], v[80:81], v[76:77], v[84:85] op_sel:[1,1,0] op_sel_hi:[1,0,1] neg_lo:[0,0,1] neg_hi:[0,0,1]
	s_nop 0
	v_add_f32_e32 v80, v82, v84

.LBB0_877:
	v_add_u32_e32 v13, s69, v174
	s_and_b64 vcc, exec, s[0:1]
	v_lshl_or_b32 v80, v13, 5, v140
	s_cbranch_vccnz .LBB0_879
	v_mov_b32_e32 v81, v135
	v_lshl_add_u64 v[68:69], v[80:81], 3, s[24:25]
	v_mov_b64_e32 v[68:69], v[234:235]
	v_pk_mul_f32 v[86:87], v[82:83], v[68:69] op_sel_hi:[0,1]
	v_pk_mul_f32 v[84:85], v[82:83], v[68:69] op_sel:[1,1] op_sel_hi:[1,0]
	v_pk_fma_f32 v[82:83], v[82:83], v[68:69], v[86:87] op_sel:[1,1,0] op_sel_hi:[1,0,1] neg_lo:[0,0,1] neg_hi:[0,0,1]
	s_nop 0
	v_add_f32_e32 v82, v84, v86

.LBB0_881:
	v_add_u32_e32 v13, s69, v175
	s_and_b64 vcc, exec, s[0:1]
	v_lshl_or_b32 v82, v13, 5, v140
	s_cbranch_vccnz .LBB0_883
	v_mov_b32_e32 v83, v135
	v_lshl_add_u64 v[66:67], v[82:83], 3, s[24:25]
	v_mov_b64_e32 v[66:67], v[236:237]
	v_pk_mul_f32 v[88:89], v[84:85], v[66:67] op_sel_hi:[0,1]
	v_pk_mul_f32 v[86:87], v[84:85], v[66:67] op_sel:[1,1] op_sel_hi:[1,0]
	v_pk_fma_f32 v[84:85], v[84:85], v[66:67], v[88:89] op_sel:[1,1,0] op_sel_hi:[1,0,1] neg_lo:[0,0,1] neg_hi:[0,0,1]
	s_nop 0
	v_add_f32_e32 v84, v86, v88

.LBB0_885:
	v_add_u32_e32 v13, s69, v176
	s_and_b64 vcc, exec, s[0:1]
	v_lshl_or_b32 v84, v13, 5, v140
	s_cbranch_vccnz .LBB0_887
	v_mov_b32_e32 v85, v135
	v_lshl_add_u64 v[64:65], v[84:85], 3, s[24:25]
	v_mov_b64_e32 v[64:65], v[238:239]
	v_pk_mul_f32 v[90:91], v[86:87], v[64:65] op_sel_hi:[0,1]
	v_pk_mul_f32 v[88:89], v[86:87], v[64:65] op_sel:[1,1] op_sel_hi:[1,0]
	v_pk_fma_f32 v[86:87], v[86:87], v[64:65], v[90:91] op_sel:[1,1,0] op_sel_hi:[1,0,1] neg_lo:[0,0,1] neg_hi:[0,0,1]
	s_nop 0
	v_add_f32_e32 v86, v88, v90

.LBB0_889:
	v_add_u32_e32 v13, s69, v177
	s_and_b64 vcc, exec, s[0:1]
	v_lshl_or_b32 v86, v13, 5, v140
	s_cbranch_vccnz .LBB0_891
	v_mov_b32_e32 v87, v135
	v_lshl_add_u64 v[56:57], v[86:87], 3, s[24:25]
	v_mov_b64_e32 v[56:57], v[240:241]
	v_pk_mul_f32 v[92:93], v[88:89], v[56:57] op_sel_hi:[0,1]
	v_pk_mul_f32 v[90:91], v[88:89], v[56:57] op_sel:[1,1] op_sel_hi:[1,0]
	v_pk_fma_f32 v[88:89], v[88:89], v[56:57], v[92:93] op_sel:[1,1,0] op_sel_hi:[1,0,1] neg_lo:[0,0,1] neg_hi:[0,0,1]
	s_nop 0
	v_add_f32_e32 v88, v90, v92

.LBB0_893:
	v_add_u32_e32 v13, s69, v178
	s_and_b64 vcc, exec, s[0:1]
	v_lshl_or_b32 v88, v13, 5, v140
	s_cbranch_vccnz .LBB0_895
	v_mov_b32_e32 v89, v135
	v_lshl_add_u64 v[54:55], v[88:89], 3, s[24:25]
	v_mov_b64_e32 v[54:55], v[242:243]
	v_pk_mul_f32 v[94:95], v[90:91], v[54:55] op_sel_hi:[0,1]
	v_pk_mul_f32 v[92:93], v[90:91], v[54:55] op_sel:[1,1] op_sel_hi:[1,0]
	v_pk_fma_f32 v[90:91], v[90:91], v[54:55], v[94:95] op_sel:[1,1,0] op_sel_hi:[1,0,1] neg_lo:[0,0,1] neg_hi:[0,0,1]
	s_nop 0
	v_add_f32_e32 v90, v92, v94

.LBB0_897:
	v_add_u32_e32 v13, s69, v179
	s_and_b64 vcc, exec, s[0:1]
	v_lshl_or_b32 v90, v13, 5, v140
	s_cbranch_vccnz .LBB0_899
	v_mov_b32_e32 v91, v135
	v_lshl_add_u64 v[52:53], v[90:91], 3, s[24:25]
	v_mov_b64_e32 v[52:53], v[244:245]
	v_pk_mul_f32 v[96:97], v[92:93], v[52:53] op_sel_hi:[0,1]
	v_pk_mul_f32 v[94:95], v[92:93], v[52:53] op_sel:[1,1] op_sel_hi:[1,0]
	v_pk_fma_f32 v[92:93], v[92:93], v[52:53], v[96:97] op_sel:[1,1,0] op_sel_hi:[1,0,1] neg_lo:[0,0,1] neg_hi:[0,0,1]
	s_nop 0
	v_add_f32_e32 v92, v94, v96

.LBB0_901:
	v_add_u32_e32 v13, s69, v180
	s_and_b64 vcc, exec, s[0:1]
	v_lshl_or_b32 v92, v13, 5, v140
	s_cbranch_vccnz .LBB0_903
	v_mov_b32_e32 v93, v135
	v_lshl_add_u64 v[50:51], v[92:93], 3, s[24:25]
	v_mov_b64_e32 v[50:51], v[246:247]
	v_pk_mul_f32 v[98:99], v[94:95], v[50:51] op_sel_hi:[0,1]
	v_pk_mul_f32 v[96:97], v[94:95], v[50:51] op_sel:[1,1] op_sel_hi:[1,0]
	v_pk_fma_f32 v[94:95], v[94:95], v[50:51], v[98:99] op_sel:[1,1,0] op_sel_hi:[1,0,1] neg_lo:[0,0,1] neg_hi:[0,0,1]
	s_nop 0
	v_add_f32_e32 v94, v96, v98

.LBB0_905:
	v_add_u32_e32 v13, s69, v181
	s_and_b64 vcc, exec, s[0:1]
	v_lshl_or_b32 v94, v13, 5, v140
	s_cbranch_vccnz .LBB0_907
	v_mov_b32_e32 v95, v135
	v_lshl_add_u64 v[48:49], v[94:95], 3, s[24:25]
	v_mov_b64_e32 v[48:49], v[248:249]
	v_pk_mul_f32 v[116:117], v[96:97], v[48:49] op_sel_hi:[0,1]
	v_pk_mul_f32 v[98:99], v[96:97], v[48:49] op_sel:[1,1] op_sel_hi:[1,0]
	v_pk_fma_f32 v[96:97], v[96:97], v[48:49], v[116:117] op_sel:[1,1,0] op_sel_hi:[1,0,1] neg_lo:[0,0,1] neg_hi:[0,0,1]
	s_nop 0
	v_add_f32_e32 v96, v98, v116

.LBB0_909:
	v_add_u32_e32 v13, s69, v182
	s_and_b64 vcc, exec, s[0:1]
	v_lshl_or_b32 v46, v13, 5, v140
	s_cbranch_vccnz .LBB0_911
	v_mov_b32_e32 v47, v135
	v_lshl_add_u64 v[116:117], v[46:47], 3, s[24:25]
	v_mov_b64_e32 v[116:117], v[250:251]
	v_pk_mul_f32 v[120:121], v[98:99], v[116:117] op_sel_hi:[0,1]
	v_pk_mul_f32 v[118:119], v[98:99], v[116:117] op_sel:[1,1] op_sel_hi:[1,0]
	v_pk_fma_f32 v[98:99], v[98:99], v[116:117], v[120:121] op_sel:[1,1,0] op_sel_hi:[1,0,1] neg_lo:[0,0,1] neg_hi:[0,0,1]
	s_nop 0
	v_add_f32_e32 v98, v118, v120

.LBB0_913:
	s_and_b64 vcc, exec, s[0:1]
	s_cbranch_vccnz .LBB0_915
	v_mov_b32_e32 v13, v135
	v_lshl_add_u64 v[12:13], v[12:13], 3, s[24:25]
	v_mov_b64_e32 v[12:13], v[144:145]
	v_pk_mul_f32 v[116:117], v[44:45], v[12:13] op_sel_hi:[0,1]
	v_pk_mul_f32 v[98:99], v[44:45], v[12:13] op_sel:[1,1] op_sel_hi:[1,0]
	v_pk_fma_f32 v[44:45], v[44:45], v[12:13], v[116:117] op_sel:[1,1,0] op_sel_hi:[1,0,1] neg_lo:[0,0,1] neg_hi:[0,0,1]
	s_nop 0
	v_add_f32_e32 v44, v98, v116

.LBB0_917:
	s_and_b64 vcc, exec, s[0:1]
	s_cbranch_vccnz .LBB0_919
	v_mov_b32_e32 v27, v135
	v_lshl_add_u64 v[24:25], v[26:27], 3, s[24:25]
	v_mov_b64_e32 v[24:25], v[146:147]
	v_pk_mul_f32 v[42:43], v[12:13], v[24:25] op_sel_hi:[0,1]
	v_pk_mul_f32 v[26:27], v[12:13], v[24:25] op_sel:[1,1] op_sel_hi:[1,0]
	v_pk_fma_f32 v[12:13], v[12:13], v[24:25], v[42:43] op_sel:[1,1,0] op_sel_hi:[1,0,1] neg_lo:[0,0,1] neg_hi:[0,0,1]
	s_nop 0
	v_add_f32_e32 v12, v26, v42

.LBB0_921:
	s_and_b64 vcc, exec, s[0:1]
	s_cbranch_vccnz .LBB0_923
	v_mov_b32_e32 v31, v135
	v_lshl_add_u64 v[14:15], v[30:31], 3, s[24:25]
	v_mov_b64_e32 v[14:15], v[184:185]
	v_pk_mul_f32 v[26:27], v[12:13], v[14:15] op_sel_hi:[0,1]
	v_pk_mul_f32 v[24:25], v[12:13], v[14:15] op_sel:[1,1] op_sel_hi:[1,0]
	v_pk_fma_f32 v[12:13], v[12:13], v[14:15], v[26:27] op_sel:[1,1,0] op_sel_hi:[1,0,1] neg_lo:[0,0,1] neg_hi:[0,0,1]
	s_nop 0
	v_add_f32_e32 v12, v24, v26

.LBB0_925:
	s_and_b64 vcc, exec, s[0:1]
	s_cbranch_vccnz .LBB0_927
	v_mov_b32_e32 v61, v135
	v_lshl_add_u64 v[14:15], v[60:61], 3, s[24:25]
	v_mov_b64_e32 v[14:15], v[186:187]
	v_pk_mul_f32 v[26:27], v[12:13], v[14:15] op_sel_hi:[0,1]
	v_pk_mul_f32 v[24:25], v[12:13], v[14:15] op_sel:[1,1] op_sel_hi:[1,0]
	v_pk_fma_f32 v[12:13], v[12:13], v[14:15], v[26:27] op_sel:[1,1,0] op_sel_hi:[1,0,1] neg_lo:[0,0,1] neg_hi:[0,0,1]
	s_nop 0
	v_add_f32_e32 v12, v24, v26

.LBB0_929:
	s_and_b64 vcc, exec, s[0:1]
	s_cbranch_vccnz .LBB0_931
	v_mov_b32_e32 v71, v135
	v_lshl_add_u64 v[14:15], v[70:71], 3, s[24:25]
	v_mov_b64_e32 v[14:15], v[226:227]
	v_pk_mul_f32 v[26:27], v[12:13], v[14:15] op_sel_hi:[0,1]
	v_pk_mul_f32 v[24:25], v[12:13], v[14:15] op_sel:[1,1] op_sel_hi:[1,0]
	v_pk_fma_f32 v[12:13], v[12:13], v[14:15], v[26:27] op_sel:[1,1,0] op_sel_hi:[1,0,1] neg_lo:[0,0,1] neg_hi:[0,0,1]
	s_nop 0
	v_add_f32_e32 v12, v24, v26

.LBB0_933:
	s_and_b64 vcc, exec, s[0:1]
	s_cbranch_vccnz .LBB0_935
	v_mov_b32_e32 v75, v135
	v_lshl_add_u64 v[14:15], v[74:75], 3, s[24:25]
	v_mov_b64_e32 v[14:15], v[230:231]
	v_pk_mul_f32 v[26:27], v[12:13], v[14:15] op_sel_hi:[0,1]
	v_pk_mul_f32 v[24:25], v[12:13], v[14:15] op_sel:[1,1] op_sel_hi:[1,0]
	v_pk_fma_f32 v[12:13], v[12:13], v[14:15], v[26:27] op_sel:[1,1,0] op_sel_hi:[1,0,1] neg_lo:[0,0,1] neg_hi:[0,0,1]
	s_nop 0
	v_add_f32_e32 v12, v24, v26

.LBB0_937:
	s_and_b64 vcc, exec, s[0:1]
	s_cbranch_vccnz .LBB0_939
	v_mov_b32_e32 v79, v135
	v_lshl_add_u64 v[14:15], v[78:79], 3, s[24:25]
	v_mov_b64_e32 v[14:15], v[232:233]
	v_pk_mul_f32 v[26:27], v[12:13], v[14:15] op_sel_hi:[0,1]
	v_pk_mul_f32 v[24:25], v[12:13], v[14:15] op_sel:[1,1] op_sel_hi:[1,0]
	v_pk_fma_f32 v[12:13], v[12:13], v[14:15], v[26:27] op_sel:[1,1,0] op_sel_hi:[1,0,1] neg_lo:[0,0,1] neg_hi:[0,0,1]
	s_nop 0
	v_add_f32_e32 v12, v24, v26

.LBB0_941:
	s_and_b64 vcc, exec, s[0:1]
	s_cbranch_vccnz .LBB0_943
	v_mov_b32_e32 v81, v135
	v_lshl_add_u64 v[14:15], v[80:81], 3, s[24:25]
	v_mov_b64_e32 v[14:15], v[234:235]
	v_pk_mul_f32 v[24:25], v[12:13], v[14:15] op_sel_hi:[0,1]
	v_pk_mul_f32 v[22:23], v[12:13], v[14:15] op_sel:[1,1] op_sel_hi:[1,0]
	v_pk_fma_f32 v[12:13], v[12:13], v[14:15], v[24:25] op_sel:[1,1,0] op_sel_hi:[1,0,1] neg_lo:[0,0,1] neg_hi:[0,0,1]
	s_nop 0
	v_add_f32_e32 v12, v22, v24

.LBB0_945:
	s_and_b64 vcc, exec, s[0:1]
	s_cbranch_vccnz .LBB0_947
	v_mov_b32_e32 v83, v135
	v_lshl_add_u64 v[14:15], v[82:83], 3, s[24:25]
	v_mov_b64_e32 v[14:15], v[236:237]
	v_pk_mul_f32 v[22:23], v[12:13], v[14:15] op_sel_hi:[0,1]
	v_pk_mul_f32 v[20:21], v[12:13], v[14:15] op_sel:[1,1] op_sel_hi:[1,0]
	v_pk_fma_f32 v[12:13], v[12:13], v[14:15], v[22:23] op_sel:[1,1,0] op_sel_hi:[1,0,1] neg_lo:[0,0,1] neg_hi:[0,0,1]
	s_nop 0
	v_add_f32_e32 v12, v20, v22

.LBB0_949:
	s_and_b64 vcc, exec, s[0:1]
	s_cbranch_vccnz .LBB0_951
	v_mov_b32_e32 v85, v135
	v_lshl_add_u64 v[14:15], v[84:85], 3, s[24:25]
	v_mov_b64_e32 v[14:15], v[238:239]
	v_pk_mul_f32 v[20:21], v[12:13], v[14:15] op_sel_hi:[0,1]
	v_pk_mul_f32 v[18:19], v[12:13], v[14:15] op_sel:[1,1] op_sel_hi:[1,0]
	v_pk_fma_f32 v[12:13], v[12:13], v[14:15], v[20:21] op_sel:[1,1,0] op_sel_hi:[1,0,1] neg_lo:[0,0,1] neg_hi:[0,0,1]
	s_nop 0
	v_add_f32_e32 v12, v18, v20

.LBB0_953:
	s_and_b64 vcc, exec, s[0:1]
	s_cbranch_vccnz .LBB0_955
	v_mov_b32_e32 v87, v135
	v_lshl_add_u64 v[14:15], v[86:87], 3, s[24:25]
	v_mov_b64_e32 v[14:15], v[240:241]
	v_pk_mul_f32 v[18:19], v[12:13], v[14:15] op_sel_hi:[0,1]
	v_pk_mul_f32 v[16:17], v[12:13], v[14:15] op_sel:[1,1] op_sel_hi:[1,0]
	v_pk_fma_f32 v[12:13], v[12:13], v[14:15], v[18:19] op_sel:[1,1,0] op_sel_hi:[1,0,1] neg_lo:[0,0,1] neg_hi:[0,0,1]
	s_nop 0
	v_add_f32_e32 v12, v16, v18

.LBB0_957:
	s_and_b64 vcc, exec, s[0:1]
	s_cbranch_vccnz .LBB0_959
	v_mov_b32_e32 v89, v135
	v_lshl_add_u64 v[12:13], v[88:89], 3, s[24:25]
	v_mov_b64_e32 v[12:13], v[242:243]
	v_pk_mul_f32 v[16:17], v[8:9], v[12:13] op_sel_hi:[0,1]
	v_pk_mul_f32 v[14:15], v[8:9], v[12:13] op_sel:[1,1] op_sel_hi:[1,0]
	v_pk_fma_f32 v[8:9], v[8:9], v[12:13], v[16:17] op_sel:[1,1,0] op_sel_hi:[1,0,1] neg_lo:[0,0,1] neg_hi:[0,0,1]
	s_nop 0
	v_add_f32_e32 v8, v14, v16

.LBB0_961:
	s_and_b64 vcc, exec, s[0:1]
	s_cbranch_vccnz .LBB0_963
	v_mov_b32_e32 v91, v135
	v_lshl_add_u64 v[8:9], v[90:91], 3, s[24:25]
	v_mov_b64_e32 v[8:9], v[244:245]
	v_pk_mul_f32 v[14:15], v[6:7], v[8:9] op_sel_hi:[0,1]
	v_pk_mul_f32 v[12:13], v[6:7], v[8:9] op_sel:[1,1] op_sel_hi:[1,0]
	v_pk_fma_f32 v[6:7], v[6:7], v[8:9], v[14:15] op_sel:[1,1,0] op_sel_hi:[1,0,1] neg_lo:[0,0,1] neg_hi:[0,0,1]
	s_nop 0
	v_add_f32_e32 v6, v12, v14

.LBB0_965:
	s_and_b64 vcc, exec, s[0:1]
	s_cbranch_vccnz .LBB0_967
	v_mov_b32_e32 v93, v135
	v_lshl_add_u64 v[6:7], v[92:93], 3, s[24:25]
	v_mov_b64_e32 v[6:7], v[246:247]
	v_pk_mul_f32 v[12:13], v[4:5], v[6:7] op_sel_hi:[0,1]
	v_pk_mul_f32 v[8:9], v[4:5], v[6:7] op_sel:[1,1] op_sel_hi:[1,0]
	v_pk_fma_f32 v[4:5], v[4:5], v[6:7], v[12:13] op_sel:[1,1,0] op_sel_hi:[1,0,1] neg_lo:[0,0,1] neg_hi:[0,0,1]
	s_nop 0
	v_add_f32_e32 v4, v8, v12

.LBB0_969:
	s_and_b64 vcc, exec, s[0:1]
	s_cbranch_vccnz .LBB0_971
	v_mov_b32_e32 v95, v135
	v_lshl_add_u64 v[4:5], v[94:95], 3, s[24:25]
	v_mov_b64_e32 v[4:5], v[248:249]
	v_pk_mul_f32 v[8:9], v[2:3], v[4:5] op_sel_hi:[0,1]
	v_pk_mul_f32 v[6:7], v[2:3], v[4:5] op_sel:[1,1] op_sel_hi:[1,0]
	v_pk_fma_f32 v[2:3], v[2:3], v[4:5], v[8:9] op_sel:[1,1,0] op_sel_hi:[1,0,1] neg_lo:[0,0,1] neg_hi:[0,0,1]
	s_nop 0
	v_add_f32_e32 v2, v6, v8

.LBB0_973:
	s_and_b64 vcc, exec, s[0:1]
	s_cbranch_vccnz .LBB0_826
	v_mov_b32_e32 v47, v135
	v_lshl_add_u64 v[2:3], v[46:47], 3, s[24:25]
	v_mov_b64_e32 v[2:3], v[250:251]
	v_pk_mul_f32 v[6:7], v[0:1], v[2:3] op_sel_hi:[0,1]
	v_pk_mul_f32 v[4:5], v[0:1], v[2:3] op_sel:[1,1] op_sel_hi:[1,0]
	v_pk_fma_f32 v[0:1], v[0:1], v[2:3], v[6:7] op_sel:[1,1,0] op_sel_hi:[1,0,1] neg_lo:[0,0,1] neg_hi:[0,0,1]
	s_nop 0
	v_add_f32_e32 v0, v4, v6
	s_branch .LBB0_826
